# phase 0 rmsnorm: four rows per trip (scalar row addresses, 16 loads in flight, interleaved wave reductions)
# baseline (speedup 1.0000x reference)
.Lr0_blk:
	v_readfirstlane_b32 s62, v18
	s_add_i32 s62, s62, 0x4080
	s_mul_i32 s63, s8, 3
	s_add_i32 s63, s63, s62
	s_cmpk_lt_i32 s63, 0x4280
	s_cbranch_scc0 .Lr0_done
	s_mov_b32 s64, s62
	s_cmpk_gt_i32 s64, 0x407f
	s_cbranch_scc1 .Lr0_s0
	s_mul_hi_i32 s65, s64, 0xfe03f81
	s_lshr_b32 s66, s65, 31
	s_ashr_i32 s65, s65, 7
	s_add_i32 s65, s65, s66
	s_mul_i32 s66, s65, 0x810
	s_sub_i32 s66, s64, s66
	s_cmpk_gt_i32 s66, 15
	s_cbranch_scc0 .Lr0_p0
	s_sub_i32 s66, s66, 16
	s_lshl_b32 s66, s66, 12
	s_lshl_b32 s65, s65, 23
	s_add_u32 s66, s66, s65
	s_add_u32 s52, s36, s66
	s_addc_u32 s53, s37, 0
	s_branch .Lr0_e0
.Lr0_p0:
	s_lshl_b32 s66, s66, 12
	s_add_u32 s52, s48, s66
	s_addc_u32 s53, s49, 0
	s_branch .Lr0_e0
.Lr0_s0:
	s_sub_i32 s66, s64, 0x4080
	s_lshl_b32 s66, s66, 12
	s_add_u32 s52, s38, s66
	s_addc_u32 s53, s39, 0
.Lr0_e0:
	global_load_dwordx4 v[64:67], v22, s[52:53]
	global_load_dwordx4 v[68:71], v22, s[52:53] offset:1024
	global_load_dwordx4 v[72:75], v22, s[52:53] offset:2048
	global_load_dwordx4 v[76:79], v22, s[52:53] offset:3072
	s_add_i32 s64, s64, s8
	s_cmpk_gt_i32 s64, 0x407f
	s_cbranch_scc1 .Lr0_s1
	s_mul_hi_i32 s65, s64, 0xfe03f81
	s_lshr_b32 s66, s65, 31
	s_ashr_i32 s65, s65, 7
	s_add_i32 s65, s65, s66
	s_mul_i32 s66, s65, 0x810
	s_sub_i32 s66, s64, s66
	s_cmpk_gt_i32 s66, 15
	s_cbranch_scc0 .Lr0_p1
	s_sub_i32 s66, s66, 16
	s_lshl_b32 s66, s66, 12
	s_lshl_b32 s65, s65, 23
	s_add_u32 s66, s66, s65
	s_add_u32 s54, s36, s66
	s_addc_u32 s55, s37, 0
	s_branch .Lr0_e1
.Lr0_p1:
	s_lshl_b32 s66, s66, 12
	s_add_u32 s54, s48, s66
	s_addc_u32 s55, s49, 0
	s_branch .Lr0_e1
.Lr0_s1:
	s_sub_i32 s66, s64, 0x4080
	s_lshl_b32 s66, s66, 12
	s_add_u32 s54, s38, s66
	s_addc_u32 s55, s39, 0
.Lr0_e1:
	global_load_dwordx4 v[80:83], v22, s[54:55]
	global_load_dwordx4 v[84:87], v22, s[54:55] offset:1024
	global_load_dwordx4 v[88:91], v22, s[54:55] offset:2048
	global_load_dwordx4 v[92:95], v22, s[54:55] offset:3072
	s_add_i32 s64, s64, s8
	s_cmpk_gt_i32 s64, 0x407f
	s_cbranch_scc1 .Lr0_s2
	s_mul_hi_i32 s65, s64, 0xfe03f81
	s_lshr_b32 s66, s65, 31
	s_ashr_i32 s65, s65, 7
	s_add_i32 s65, s65, s66
	s_mul_i32 s66, s65, 0x810
	s_sub_i32 s66, s64, s66
	s_cmpk_gt_i32 s66, 15
	s_cbranch_scc0 .Lr0_p2
	s_sub_i32 s66, s66, 16
	s_lshl_b32 s66, s66, 12
	s_lshl_b32 s65, s65, 23
	s_add_u32 s66, s66, s65
	s_add_u32 s56, s36, s66
	s_addc_u32 s57, s37, 0
	s_branch .Lr0_e2
.Lr0_p2:
	s_lshl_b32 s66, s66, 12
	s_add_u32 s56, s48, s66
	s_addc_u32 s57, s49, 0
	s_branch .Lr0_e2
.Lr0_s2:
	s_sub_i32 s66, s64, 0x4080
	s_lshl_b32 s66, s66, 12
	s_add_u32 s56, s38, s66
	s_addc_u32 s57, s39, 0
.Lr0_e2:
	global_load_dwordx4 v[96:99], v22, s[56:57]
	global_load_dwordx4 v[100:103], v22, s[56:57] offset:1024
	global_load_dwordx4 v[104:107], v22, s[56:57] offset:2048
	global_load_dwordx4 v[108:111], v22, s[56:57] offset:3072
	s_add_i32 s64, s64, s8
	s_cmpk_gt_i32 s64, 0x407f
	s_cbranch_scc1 .Lr0_s3
	s_mul_hi_i32 s65, s64, 0xfe03f81
	s_lshr_b32 s66, s65, 31
	s_ashr_i32 s65, s65, 7
	s_add_i32 s65, s65, s66
	s_mul_i32 s66, s65, 0x810
	s_sub_i32 s66, s64, s66
	s_cmpk_gt_i32 s66, 15
	s_cbranch_scc0 .Lr0_p3
	s_sub_i32 s66, s66, 16
	s_lshl_b32 s66, s66, 12
	s_lshl_b32 s65, s65, 23
	s_add_u32 s66, s66, s65
	s_add_u32 s58, s36, s66
	s_addc_u32 s59, s37, 0
	s_branch .Lr0_e3
.Lr0_p3:
	s_lshl_b32 s66, s66, 12
	s_add_u32 s58, s48, s66
	s_addc_u32 s59, s49, 0
	s_branch .Lr0_e3
.Lr0_s3:
	s_sub_i32 s66, s64, 0x4080
	s_lshl_b32 s66, s66, 12
	s_add_u32 s58, s38, s66
	s_addc_u32 s59, s39, 0
.Lr0_e3:
	global_load_dwordx4 v[112:115], v22, s[58:59]
	global_load_dwordx4 v[116:119], v22, s[58:59] offset:1024
	global_load_dwordx4 v[120:123], v22, s[58:59] offset:2048
	global_load_dwordx4 v[124:127], v22, s[58:59] offset:3072
	v_lshl_add_u64 v[48:49], v[20:21], 0, s[10:11]
	v_lshl_add_u64 v[50:51], v[48:49], 0, s[10:11]
	v_lshl_add_u64 v[52:53], v[50:51], 0, s[10:11]
	s_waitcnt vmcnt(12)
	v_pk_mul_f32 v[54:55], v[64:65], v[64:65]
	v_pk_fma_f32 v[54:55], v[66:67], v[66:67], v[54:55]
	v_pk_fma_f32 v[54:55], v[68:69], v[68:69], v[54:55]
	v_pk_fma_f32 v[54:55], v[70:71], v[70:71], v[54:55]
	v_pk_fma_f32 v[54:55], v[72:73], v[72:73], v[54:55]
	v_pk_fma_f32 v[54:55], v[74:75], v[74:75], v[54:55]
	v_pk_fma_f32 v[54:55], v[76:77], v[76:77], v[54:55]
	v_pk_fma_f32 v[54:55], v[78:79], v[78:79], v[54:55]
	s_nop 0
	v_add_f32_e32 v56, v54, v55
	s_waitcnt vmcnt(8)
	v_pk_mul_f32 v[54:55], v[80:81], v[80:81]
	v_pk_fma_f32 v[54:55], v[82:83], v[82:83], v[54:55]
	v_pk_fma_f32 v[54:55], v[84:85], v[84:85], v[54:55]
	v_pk_fma_f32 v[54:55], v[86:87], v[86:87], v[54:55]
	v_pk_fma_f32 v[54:55], v[88:89], v[88:89], v[54:55]
	v_pk_fma_f32 v[54:55], v[90:91], v[90:91], v[54:55]
	v_pk_fma_f32 v[54:55], v[92:93], v[92:93], v[54:55]
	v_pk_fma_f32 v[54:55], v[94:95], v[94:95], v[54:55]
	s_nop 0
	v_add_f32_e32 v57, v54, v55
	s_waitcnt vmcnt(4)
	v_pk_mul_f32 v[54:55], v[96:97], v[96:97]
	v_pk_fma_f32 v[54:55], v[98:99], v[98:99], v[54:55]
	v_pk_fma_f32 v[54:55], v[100:101], v[100:101], v[54:55]
	v_pk_fma_f32 v[54:55], v[102:103], v[102:103], v[54:55]
	v_pk_fma_f32 v[54:55], v[104:105], v[104:105], v[54:55]
	v_pk_fma_f32 v[54:55], v[106:107], v[106:107], v[54:55]
	v_pk_fma_f32 v[54:55], v[108:109], v[108:109], v[54:55]
	v_pk_fma_f32 v[54:55], v[110:111], v[110:111], v[54:55]
	s_nop 0
	v_add_f32_e32 v58, v54, v55
	s_waitcnt vmcnt(0)
	v_pk_mul_f32 v[54:55], v[112:113], v[112:113]
	v_pk_fma_f32 v[54:55], v[114:115], v[114:115], v[54:55]
	v_pk_fma_f32 v[54:55], v[116:117], v[116:117], v[54:55]
	v_pk_fma_f32 v[54:55], v[118:119], v[118:119], v[54:55]
	v_pk_fma_f32 v[54:55], v[120:121], v[120:121], v[54:55]
	v_pk_fma_f32 v[54:55], v[122:123], v[122:123], v[54:55]
	v_pk_fma_f32 v[54:55], v[124:125], v[124:125], v[54:55]
	v_pk_fma_f32 v[54:55], v[126:127], v[126:127], v[54:55]
	s_nop 0
	v_add_f32_e32 v59, v54, v55
	ds_bpermute_b32 v60, v28, v56
	ds_bpermute_b32 v61, v28, v57
	ds_bpermute_b32 v62, v28, v58
	ds_bpermute_b32 v63, v28, v59
	s_waitcnt lgkmcnt(0)
	v_add_f32_e32 v56, v56, v60
	v_add_f32_e32 v57, v57, v61
	v_add_f32_e32 v58, v58, v62
	v_add_f32_e32 v59, v59, v63
	ds_bpermute_b32 v60, v29, v56
	ds_bpermute_b32 v61, v29, v57
	ds_bpermute_b32 v62, v29, v58
	ds_bpermute_b32 v63, v29, v59
	s_waitcnt lgkmcnt(0)
	v_add_f32_e32 v56, v56, v60
	v_add_f32_e32 v57, v57, v61
	v_add_f32_e32 v58, v58, v62
	v_add_f32_e32 v59, v59, v63
	ds_bpermute_b32 v60, v30, v56
	ds_bpermute_b32 v61, v30, v57
	ds_bpermute_b32 v62, v30, v58
	ds_bpermute_b32 v63, v30, v59
	s_waitcnt lgkmcnt(0)
	v_add_f32_e32 v56, v56, v60
	v_add_f32_e32 v57, v57, v61
	v_add_f32_e32 v58, v58, v62
	v_add_f32_e32 v59, v59, v63
	ds_bpermute_b32 v60, v31, v56
	ds_bpermute_b32 v61, v31, v57
	ds_bpermute_b32 v62, v31, v58
	ds_bpermute_b32 v63, v31, v59
	s_waitcnt lgkmcnt(0)
	v_add_f32_e32 v56, v56, v60
	v_add_f32_e32 v57, v57, v61
	v_add_f32_e32 v58, v58, v62
	v_add_f32_e32 v59, v59, v63
	ds_bpermute_b32 v60, v32, v56
	ds_bpermute_b32 v61, v32, v57
	ds_bpermute_b32 v62, v32, v58
	ds_bpermute_b32 v63, v32, v59
	s_waitcnt lgkmcnt(0)
	v_add_f32_e32 v56, v56, v60
	v_add_f32_e32 v57, v57, v61
	v_add_f32_e32 v58, v58, v62
	v_add_f32_e32 v59, v59, v63
	ds_bpermute_b32 v60, v33, v56
	ds_bpermute_b32 v61, v33, v57
	ds_bpermute_b32 v62, v33, v58
	ds_bpermute_b32 v63, v33, v59
	s_waitcnt lgkmcnt(0)
	v_add_f32_e32 v56, v56, v60
	v_add_f32_e32 v57, v57, v61
	v_add_f32_e32 v58, v58, v62
	v_add_f32_e32 v59, v59, v63
	v_fmamk_f32 v56, v56, 0x3a800000, v34
	v_mul_f32_e32 v60, 0x4b800000, v56
	v_cmp_gt_f32_e32 vcc, s15, v56
	s_nop 1
	v_cndmask_b32_e32 v56, v56, v60, vcc
	v_rsq_f32_e32 v56, v56
	s_nop 1
	v_mul_f32_e32 v60, 0x45800000, v56
	v_cndmask_b32_e32 v56, v56, v60, vcc
	v_fmamk_f32 v57, v57, 0x3a800000, v34
	v_mul_f32_e32 v61, 0x4b800000, v57
	v_cmp_gt_f32_e32 vcc, s15, v57
	s_nop 1
	v_cndmask_b32_e32 v57, v57, v61, vcc
	v_rsq_f32_e32 v57, v57
	s_nop 1
	v_mul_f32_e32 v61, 0x45800000, v57
	v_cndmask_b32_e32 v57, v57, v61, vcc
	v_fmamk_f32 v58, v58, 0x3a800000, v34
	v_mul_f32_e32 v62, 0x4b800000, v58
	v_cmp_gt_f32_e32 vcc, s15, v58
	s_nop 1
	v_cndmask_b32_e32 v58, v58, v62, vcc
	v_rsq_f32_e32 v58, v58
	s_nop 1
	v_mul_f32_e32 v62, 0x45800000, v58
	v_cndmask_b32_e32 v58, v58, v62, vcc
	v_fmamk_f32 v59, v59, 0x3a800000, v34
	v_mul_f32_e32 v63, 0x4b800000, v59
	v_cmp_gt_f32_e32 vcc, s15, v59
	s_nop 1
	v_cndmask_b32_e32 v59, v59, v63, vcc
	v_rsq_f32_e32 v59, v59
	s_nop 1
	v_mul_f32_e32 v63, 0x45800000, v59
	v_cndmask_b32_e32 v59, v59, v63, vcc
	v_mov_b32_e32 v54, v56
	s_nop 0
	v_pk_mul_f32 v[64:65], v[64:65], v[54:55] op_sel_hi:[1,0]
	v_pk_mul_f32 v[66:67], v[66:67], v[54:55] op_sel_hi:[1,0]
	v_pk_mul_f32 v[68:69], v[68:69], v[54:55] op_sel_hi:[1,0]
	v_pk_mul_f32 v[70:71], v[70:71], v[54:55] op_sel_hi:[1,0]
	v_pk_mul_f32 v[72:73], v[72:73], v[54:55] op_sel_hi:[1,0]
	v_pk_mul_f32 v[74:75], v[74:75], v[54:55] op_sel_hi:[1,0]
	v_pk_mul_f32 v[76:77], v[76:77], v[54:55] op_sel_hi:[1,0]
	v_pk_mul_f32 v[78:79], v[78:79], v[54:55] op_sel_hi:[1,0]
	v_pk_mul_f32 v[64:65], v[0:1], v[64:65]
	v_pk_mul_f32 v[66:67], v[2:3], v[66:67]
	v_pk_mul_f32 v[68:69], v[4:5], v[68:69]
	v_pk_mul_f32 v[70:71], v[6:7], v[70:71]
	v_pk_mul_f32 v[72:73], v[8:9], v[72:73]
	v_pk_mul_f32 v[74:75], v[10:11], v[74:75]
	v_pk_mul_f32 v[76:77], v[12:13], v[76:77]
	v_pk_mul_f32 v[78:79], v[14:15], v[78:79]
	v_cvt_pk_f16_f32 v64, v64, v65
	v_cvt_pk_f16_f32 v65, v66, v67
	v_cvt_pk_f16_f32 v68, v68, v69
	v_cvt_pk_f16_f32 v69, v70, v71
	v_cvt_pk_f16_f32 v72, v72, v73
	v_cvt_pk_f16_f32 v73, v74, v75
	v_cvt_pk_f16_f32 v76, v76, v77
	v_cvt_pk_f16_f32 v77, v78, v79
	global_store_dwordx2 v[20:21], v[64:65], off
	global_store_dwordx2 v[20:21], v[68:69], off offset:512
	global_store_dwordx2 v[20:21], v[72:73], off offset:1024
	global_store_dwordx2 v[20:21], v[76:77], off offset:1536
	v_mov_b32_e32 v54, v57
	s_nop 0
	v_pk_mul_f32 v[80:81], v[80:81], v[54:55] op_sel_hi:[1,0]
	v_pk_mul_f32 v[82:83], v[82:83], v[54:55] op_sel_hi:[1,0]
	v_pk_mul_f32 v[84:85], v[84:85], v[54:55] op_sel_hi:[1,0]
	v_pk_mul_f32 v[86:87], v[86:87], v[54:55] op_sel_hi:[1,0]
	v_pk_mul_f32 v[88:89], v[88:89], v[54:55] op_sel_hi:[1,0]
	v_pk_mul_f32 v[90:91], v[90:91], v[54:55] op_sel_hi:[1,0]
	v_pk_mul_f32 v[92:93], v[92:93], v[54:55] op_sel_hi:[1,0]
	v_pk_mul_f32 v[94:95], v[94:95], v[54:55] op_sel_hi:[1,0]
	v_pk_mul_f32 v[80:81], v[0:1], v[80:81]
	v_pk_mul_f32 v[82:83], v[2:3], v[82:83]
	v_pk_mul_f32 v[84:85], v[4:5], v[84:85]
	v_pk_mul_f32 v[86:87], v[6:7], v[86:87]
	v_pk_mul_f32 v[88:89], v[8:9], v[88:89]
	v_pk_mul_f32 v[90:91], v[10:11], v[90:91]
	v_pk_mul_f32 v[92:93], v[12:13], v[92:93]
	v_pk_mul_f32 v[94:95], v[14:15], v[94:95]
	v_cvt_pk_f16_f32 v80, v80, v81
	v_cvt_pk_f16_f32 v81, v82, v83
	v_cvt_pk_f16_f32 v84, v84, v85
	v_cvt_pk_f16_f32 v85, v86, v87
	v_cvt_pk_f16_f32 v88, v88, v89
	v_cvt_pk_f16_f32 v89, v90, v91
	v_cvt_pk_f16_f32 v92, v92, v93
	v_cvt_pk_f16_f32 v93, v94, v95
	global_store_dwordx2 v[48:49], v[80:81], off
	global_store_dwordx2 v[48:49], v[84:85], off offset:512
	global_store_dwordx2 v[48:49], v[88:89], off offset:1024
	global_store_dwordx2 v[48:49], v[92:93], off offset:1536
	v_mov_b32_e32 v54, v58
	s_nop 0
	v_pk_mul_f32 v[96:97], v[96:97], v[54:55] op_sel_hi:[1,0]
	v_pk_mul_f32 v[98:99], v[98:99], v[54:55] op_sel_hi:[1,0]
	v_pk_mul_f32 v[100:101], v[100:101], v[54:55] op_sel_hi:[1,0]
	v_pk_mul_f32 v[102:103], v[102:103], v[54:55] op_sel_hi:[1,0]
	v_pk_mul_f32 v[104:105], v[104:105], v[54:55] op_sel_hi:[1,0]
	v_pk_mul_f32 v[106:107], v[106:107], v[54:55] op_sel_hi:[1,0]
	v_pk_mul_f32 v[108:109], v[108:109], v[54:55] op_sel_hi:[1,0]
	v_pk_mul_f32 v[110:111], v[110:111], v[54:55] op_sel_hi:[1,0]
	v_pk_mul_f32 v[96:97], v[0:1], v[96:97]
	v_pk_mul_f32 v[98:99], v[2:3], v[98:99]
	v_pk_mul_f32 v[100:101], v[4:5], v[100:101]
	v_pk_mul_f32 v[102:103], v[6:7], v[102:103]
	v_pk_mul_f32 v[104:105], v[8:9], v[104:105]
	v_pk_mul_f32 v[106:107], v[10:11], v[106:107]
	v_pk_mul_f32 v[108:109], v[12:13], v[108:109]
	v_pk_mul_f32 v[110:111], v[14:15], v[110:111]
	v_cvt_pk_f16_f32 v96, v96, v97
	v_cvt_pk_f16_f32 v97, v98, v99
	v_cvt_pk_f16_f32 v100, v100, v101
	v_cvt_pk_f16_f32 v101, v102, v103
	v_cvt_pk_f16_f32 v104, v104, v105
	v_cvt_pk_f16_f32 v105, v106, v107
	v_cvt_pk_f16_f32 v108, v108, v109
	v_cvt_pk_f16_f32 v109, v110, v111
	global_store_dwordx2 v[50:51], v[96:97], off
	global_store_dwordx2 v[50:51], v[100:101], off offset:512
	global_store_dwordx2 v[50:51], v[104:105], off offset:1024
	global_store_dwordx2 v[50:51], v[108:109], off offset:1536
	v_mov_b32_e32 v54, v59
	s_nop 0
	v_pk_mul_f32 v[112:113], v[112:113], v[54:55] op_sel_hi:[1,0]
	v_pk_mul_f32 v[114:115], v[114:115], v[54:55] op_sel_hi:[1,0]
	v_pk_mul_f32 v[116:117], v[116:117], v[54:55] op_sel_hi:[1,0]
	v_pk_mul_f32 v[118:119], v[118:119], v[54:55] op_sel_hi:[1,0]
	v_pk_mul_f32 v[120:121], v[120:121], v[54:55] op_sel_hi:[1,0]
	v_pk_mul_f32 v[122:123], v[122:123], v[54:55] op_sel_hi:[1,0]
	v_pk_mul_f32 v[124:125], v[124:125], v[54:55] op_sel_hi:[1,0]
	v_pk_mul_f32 v[126:127], v[126:127], v[54:55] op_sel_hi:[1,0]
	v_pk_mul_f32 v[112:113], v[0:1], v[112:113]
	v_pk_mul_f32 v[114:115], v[2:3], v[114:115]
	v_pk_mul_f32 v[116:117], v[4:5], v[116:117]
	v_pk_mul_f32 v[118:119], v[6:7], v[118:119]
	v_pk_mul_f32 v[120:121], v[8:9], v[120:121]
	v_pk_mul_f32 v[122:123], v[10:11], v[122:123]
	v_pk_mul_f32 v[124:125], v[12:13], v[124:125]
	v_pk_mul_f32 v[126:127], v[14:15], v[126:127]
	v_cvt_pk_f16_f32 v112, v112, v113
	v_cvt_pk_f16_f32 v113, v114, v115
	v_cvt_pk_f16_f32 v116, v116, v117
	v_cvt_pk_f16_f32 v117, v118, v119
	v_cvt_pk_f16_f32 v120, v120, v121
	v_cvt_pk_f16_f32 v121, v122, v123
	v_cvt_pk_f16_f32 v124, v124, v125
	v_cvt_pk_f16_f32 v125, v126, v127
	global_store_dwordx2 v[52:53], v[112:113], off
	global_store_dwordx2 v[52:53], v[116:117], off offset:512
	global_store_dwordx2 v[52:53], v[120:121], off offset:1024
	global_store_dwordx2 v[52:53], v[124:125], off offset:1536
	s_mul_i32 s63, s8, 4
	s_lshl_b64 s[64:65], s[10:11], 2
	v_add_u32_e32 v18, s63, v18
	v_lshl_add_u64 v[20:21], v[20:21], 0, s[64:65]
	s_branch .Lr0_blk
.Lr0_done:
	s_cmpk_lt_i32 s62, 0x4280
	s_cbranch_scc1 .LBB0_149
	s_branch .LBB0_156
